# in-proj k-loop: running LDS-DMA source addresses advanced behind the loads (no 64-bit add in front of each load)
# speedup vs baseline: 1.0533x; 1.0000x over previous
; #define MFMA16(a, b, c) __builtin_amdgcn_mfma_f32_16x16x32_bf16((a), (b), (c), 0, 0, 0)
; template <int EPI>
; DI void gemm_tile(const GemmArgs& ga, const EpiArgs& ea, int m0, int n0, char* lds) {
;     ...
;   for (int kt = 0; kt < nk; ++kt) {
;     if (kt + 1 < nk) asm volatile("s_waitcnt vmcnt(6)" ::: "memory");
;     else asm volatile("s_waitcnt vmcnt(0)" ::: "memory");
;     __builtin_amdgcn_s_barrier();
;     const char* Ab = lds + (kt % 3) * 24576 + wm * 128 * 64;
;     const char* Bb = lds + (kt % 3) * 24576 + 16384 + wn * 64 * 64;
;     bf16x8 af[8], bfr[4];
;     const int ch = swz64(c16, quad) << 4;
; #pragma unroll
;     for (int nt = 0; nt < 4; ++nt) bfr[nt] = *(const bf16x8*)(Bb + (nt * 16 + c16) * 64 + ch);
; #pragma unroll
;     for (int mt = 0; mt < 2; ++mt) af[mt] = *(const bf16x8*)(Ab + (mt * 16 + c16) * 64 + ch);
;     __builtin_amdgcn_sched_barrier(0);
;     if (kt + 2 < nk) dma(kt + 2, (kt + 2) % 3);
;     __builtin_amdgcn_sched_barrier(0);
; #pragma unroll
;     for (int g = 0; g < 4; ++g) {
;       if (g < 3) {
; #pragma unroll
;         for (int mt = 2 * g + 2; mt < 2 * g + 4; ++mt) af[mt] = *(const bf16x8*)(Ab + (mt * 16 + c16) * 64 + ch);
;       }
; #pragma unroll
;       for (int mt = 2 * g; mt < 2 * g + 2; ++mt)
; #pragma unroll
;         for (int nt = 0; nt < 4; ++nt) acc[mt][nt] = MFMA16(bfr[nt], af[mt], acc[mt][nt]);
;       __builtin_amdgcn_sched_barrier(0);
;     }
.LBB0_180:
	s_mul_hi_u32 s28, s27, 0xaaaaaaab
	s_lshr_b32 s28, s28, 1
	s_mul_i32 s28, s28, 0xfffee000
	v_or_b32_e32 v199, s28, v196
	v_add_u32_e32 v212, v198, v199
	s_waitcnt vmcnt(6)
	s_barrier
	v_add_u32_e32 v199, v197, v199
	ds_read_b128 v[200:203], v212 offset:16384
	ds_read_b128 v[204:207], v212 offset:17408
	ds_read_b128 v[208:211], v212 offset:18432
	ds_read_b128 v[212:215], v212 offset:19456
	ds_read_b128 v[216:219], v199
	ds_read_b128 v[220:223], v199 offset:1024
	s_add_i32 s27, s27, 1
	s_mul_i32 s28, s8, 0xab
	s_bfe_u32 s28, s28, 0x70009
	s_mul_i32 s28, s28, 3
	s_sub_i32 s28, s8, s28
	s_and_b32 s28, s28, 0xff
	s_mulk_i32 s28, 0x6000
	s_add_i32 s28, s28, 16
	s_add_i32 s29, s28, s100
	s_mov_b32 m0, s29
	s_nop 0
	global_load_lds_dwordx4 v[130:131], off
	s_add_i32 m0, s29, 0x400
	s_nop 0
	global_load_lds_dwordx4 v[132:133], off
	s_add_i32 m0, s29, 0x800
	s_nop 0
	global_load_lds_dwordx4 v[134:135], off
	s_add_i32 m0, s29, 0xc00
	s_nop 0
	global_load_lds_dwordx4 v[136:137], off
	s_add_i32 m0, s29, 0x1000
	s_nop 0
	global_load_lds_dwordx4 v[138:139], off
	s_add_i32 m0, s29, 0x1400
	s_nop 0
	global_load_lds_dwordx4 v[140:141], off
	v_lshl_add_u64 v[130:131], v[130:131], 0, 64
	v_lshl_add_u64 v[132:133], v[132:133], 0, 64
	v_lshl_add_u64 v[134:135], v[134:135], 0, 64
	v_lshl_add_u64 v[136:137], v[136:137], 0, 64
	v_lshl_add_u64 v[138:139], v[138:139], 0, 64
	v_lshl_add_u64 v[140:141], v[140:141], 0, 64
	s_waitcnt lgkmcnt(0)
	v_mfma_f32_16x16x32_bf16 v[126:129], v[200:203], v[216:219], v[126:129]
	v_mfma_f32_16x16x32_bf16 v[122:125], v[204:207], v[216:219], v[122:125]
	v_mfma_f32_16x16x32_bf16 v[118:121], v[208:211], v[216:219], v[118:121]
	v_mfma_f32_16x16x32_bf16 v[114:117], v[212:215], v[216:219], v[114:117]
	ds_read_b128 v[216:219], v199 offset:2048
	ds_read_b128 v[224:227], v199 offset:3072
	v_mfma_f32_16x16x32_bf16 v[106:109], v[200:203], v[220:223], v[106:109]
	v_mfma_f32_16x16x32_bf16 v[98:101], v[204:207], v[220:223], v[98:101]
	v_mfma_f32_16x16x32_bf16 v[86:89], v[208:211], v[220:223], v[86:89]
	v_mfma_f32_16x16x32_bf16 v[74:77], v[212:215], v[220:223], v[74:77]
	s_waitcnt lgkmcnt(0)
	v_mfma_f32_16x16x32_bf16 v[70:73], v[200:203], v[216:219], v[70:73]
	v_mfma_f32_16x16x32_bf16 v[66:69], v[204:207], v[216:219], v[66:69]
	v_mfma_f32_16x16x32_bf16 v[62:65], v[208:211], v[216:219], v[62:65]
	v_mfma_f32_16x16x32_bf16 v[58:61], v[212:215], v[216:219], v[58:61]
	ds_read_b128 v[216:219], v199 offset:4096
	ds_read_b128 v[220:223], v199 offset:5120
	v_mfma_f32_16x16x32_bf16 v[54:57], v[200:203], v[224:227], v[54:57]
	v_mfma_f32_16x16x32_bf16 v[50:53], v[204:207], v[224:227], v[50:53]
	v_mfma_f32_16x16x32_bf16 v[46:49], v[208:211], v[224:227], v[46:49]
	v_mfma_f32_16x16x32_bf16 v[42:45], v[212:215], v[224:227], v[42:45]
	s_waitcnt lgkmcnt(0)
	v_mfma_f32_16x16x32_bf16 v[38:41], v[200:203], v[216:219], v[38:41]
	v_mfma_f32_16x16x32_bf16 v[34:37], v[204:207], v[216:219], v[34:37]
	v_mfma_f32_16x16x32_bf16 v[30:33], v[208:211], v[216:219], v[30:33]
	v_mfma_f32_16x16x32_bf16 v[26:29], v[212:215], v[216:219], v[26:29]
	ds_read_b128 v[216:219], v199 offset:6144
	ds_read_b128 v[224:227], v199 offset:7168
	v_mfma_f32_16x16x32_bf16 v[22:25], v[200:203], v[220:223], v[22:25]
	v_mfma_f32_16x16x32_bf16 v[18:21], v[204:207], v[220:223], v[18:21]
	v_mfma_f32_16x16x32_bf16 v[14:17], v[208:211], v[220:223], v[14:17]
	v_mfma_f32_16x16x32_bf16 v[10:13], v[212:215], v[220:223], v[10:13]
	s_waitcnt lgkmcnt(0)
	v_mfma_f32_16x16x32_bf16 v[6:9], v[200:203], v[216:219], v[6:9]
	v_mfma_f32_16x16x32_bf16 v[2:5], v[204:207], v[216:219], v[2:5]
	v_mfma_f32_16x16x32_bf16 v[78:81], v[208:211], v[216:219], v[78:81]
	v_mfma_f32_16x16x32_bf16 v[82:85], v[212:215], v[216:219], v[82:85]
	v_mfma_f32_16x16x32_bf16 v[90:93], v[200:203], v[224:227], v[90:93]
	v_mfma_f32_16x16x32_bf16 v[94:97], v[204:207], v[224:227], v[94:97]
	v_mfma_f32_16x16x32_bf16 v[102:105], v[208:211], v[224:227], v[102:105]
	v_mfma_f32_16x16x32_bf16 v[110:113], v[212:215], v[224:227], v[110:113]
	s_add_i32 s8, s8, 1
	s_add_u32 s24, s24, 64
	s_addc_u32 s25, s25, 0
	v_add_u32_e32 v198, 0x6000, v198
	s_cmpk_eq_i32 s24, 0x780
	v_add_u32_e32 v197, 0x6000, v197
	s_cbranch_scc0 .LBB0_180
	s_waitcnt vmcnt(0)
	v_add_f32_e32 v130, 0, v146
	v_add_f32_e32 v130, v130, v147
	v_add_f32_e32 v130, v130, v156
	v_add_f32_e32 v130, v130, v157
	v_add_f32_e32 v130, v130, v158
	v_add_f32_e32 v130, v130, v159
	v_add_f32_e32 v130, v130, v160
	v_add_f32_e32 v130, v130, v161
	v_add_f32_e32 v130, v130, v162
	v_add_f32_e32 v130, v130, v163
	v_add_f32_e32 v130, v130, v164
	v_add_f32_e32 v130, v130, v165
	v_add_f32_e32 v130, v130, v166
	v_add_f32_e32 v130, v130, v168
	v_add3_u32 v147, v195, v192, v194
	v_add_f32_e32 v146, v130, v169
	s_waitcnt vmcnt(6)
	s_barrier
; #define MFMA16(a, b, c) __builtin_amdgcn_mfma_f32_16x16x32_bf16((a), (b), (c), 0, 0, 0)
; template <int EPI>
; DI void gemm_tile(const GemmArgs& ga, const EpiArgs& ea, int m0, int n0, char* lds) {
;     ...
;   for (int kt = 0; kt < nk; ++kt) {
;     if (kt + 1 < nk) asm volatile("s_waitcnt vmcnt(6)" ::: "memory");
;     else asm volatile("s_waitcnt vmcnt(0)" ::: "memory");
;     __builtin_amdgcn_s_barrier();
;     const char* Ab = lds + (kt % 3) * 24576 + wm * 128 * 64;
;     const char* Bb = lds + (kt % 3) * 24576 + 16384 + wn * 64 * 64;
;     bf16x8 af[8], bfr[4];
;     const int ch = swz64(c16, quad) << 4;
; #pragma unroll
;     for (int nt = 0; nt < 4; ++nt) bfr[nt] = *(const bf16x8*)(Bb + (nt * 16 + c16) * 64 + ch);
; #pragma unroll
;     for (int mt = 0; mt < 2; ++mt) af[mt] = *(const bf16x8*)(Ab + (mt * 16 + c16) * 64 + ch);
;     __builtin_amdgcn_sched_barrier(0);
;     if (kt + 2 < nk) dma(kt + 2, (kt + 2) % 3);
;     __builtin_amdgcn_sched_barrier(0);
; #pragma unroll
;     for (int g = 0; g < 4; ++g) {
;       if (g < 3) {
; #pragma unroll
;         for (int mt = 2 * g + 2; mt < 2 * g + 4; ++mt) af[mt] = *(const bf16x8*)(Ab + (mt * 16 + c16) * 64 + ch);
;       }
; #pragma unroll
;       for (int mt = 2 * g; mt < 2 * g + 2; ++mt)
; #pragma unroll
;         for (int nt = 0; nt < 4; ++nt) acc[mt][nt] = MFMA16(bfr[nt], af[mt], acc[mt][nt]);
;       __builtin_amdgcn_sched_barrier(0);
;     }
	ds_read_b128 v[130:133], v147 offset:16384
	ds_read_b128 v[134:137], v147 offset:17408
	ds_read_b128 v[138:141], v147 offset:18432
	ds_read_b128 v[156:159], v147 offset:19456
	v_add3_u32 v164, v193, v192, v194
	ds_read_b128 v[160:163], v164
	ds_read_b128 v[168:171], v164 offset:1024
	s_waitcnt lgkmcnt(1)
	v_mfma_f32_16x16x32_bf16 v[126:129], v[130:133], v[160:163], v[126:129]
	v_mfma_f32_16x16x32_bf16 v[122:125], v[134:137], v[160:163], v[122:125]
	v_mfma_f32_16x16x32_bf16 v[118:121], v[138:141], v[160:163], v[118:121]
	v_mfma_f32_16x16x32_bf16 v[114:117], v[156:159], v[160:163], v[114:117]
	ds_read_b128 v[160:163], v164 offset:2048
	ds_read_b128 v[188:191], v164 offset:3072
	s_waitcnt lgkmcnt(2)
	v_mfma_f32_16x16x32_bf16 v[106:109], v[130:133], v[168:171], v[106:109]
	v_mfma_f32_16x16x32_bf16 v[98:101], v[134:137], v[168:171], v[98:101]
	v_mfma_f32_16x16x32_bf16 v[86:89], v[138:141], v[168:171], v[86:89]
	v_mfma_f32_16x16x32_bf16 v[74:77], v[156:159], v[168:171], v[74:77]
	s_waitcnt lgkmcnt(1)
	v_mfma_f32_16x16x32_bf16 v[70:73], v[130:133], v[160:163], v[70:73]
	v_mfma_f32_16x16x32_bf16 v[66:69], v[134:137], v[160:163], v[66:69]
	v_mfma_f32_16x16x32_bf16 v[62:65], v[138:141], v[160:163], v[62:65]
	v_mfma_f32_16x16x32_bf16 v[58:61], v[156:159], v[160:163], v[58:61]
	ds_read_b128 v[160:163], v164 offset:4096
	ds_read_b128 v[168:171], v164 offset:5120
	s_waitcnt lgkmcnt(2)
	v_mfma_f32_16x16x32_bf16 v[54:57], v[130:133], v[188:191], v[54:57]
	v_mfma_f32_16x16x32_bf16 v[50:53], v[134:137], v[188:191], v[50:53]
	v_mfma_f32_16x16x32_bf16 v[46:49], v[138:141], v[188:191], v[46:49]
	v_mfma_f32_16x16x32_bf16 v[42:45], v[156:159], v[188:191], v[42:45]
	s_waitcnt lgkmcnt(1)
	v_mfma_f32_16x16x32_bf16 v[38:41], v[130:133], v[160:163], v[38:41]
	v_mfma_f32_16x16x32_bf16 v[34:37], v[134:137], v[160:163], v[34:37]
	v_mfma_f32_16x16x32_bf16 v[30:33], v[138:141], v[160:163], v[30:33]
	v_mfma_f32_16x16x32_bf16 v[26:29], v[156:159], v[160:163], v[26:29]
	ds_read_b128 v[160:163], v164 offset:6144
	ds_read_b128 v[188:191], v164 offset:7168
	s_waitcnt lgkmcnt(2)
	v_mfma_f32_16x16x32_bf16 v[22:25], v[130:133], v[168:171], v[22:25]
	v_mfma_f32_16x16x32_bf16 v[18:21], v[134:137], v[168:171], v[18:21]
	v_mfma_f32_16x16x32_bf16 v[14:17], v[138:141], v[168:171], v[14:17]
	v_mfma_f32_16x16x32_bf16 v[10:13], v[156:159], v[168:171], v[10:13]
	s_waitcnt lgkmcnt(1)
	v_mfma_f32_16x16x32_bf16 v[6:9], v[130:133], v[160:163], v[6:9]
	v_mfma_f32_16x16x32_bf16 v[2:5], v[134:137], v[160:163], v[2:5]
	v_mfma_f32_16x16x32_bf16 v[168:171], v[138:141], v[160:163], v[78:81]
	s_waitcnt lgkmcnt(0)
	v_mfma_f32_16x16x32_bf16 v[134:137], v[134:137], v[188:191], v[94:97]
	v_mfma_f32_16x16x32_bf16 v[138:141], v[138:141], v[188:191], v[102:105]
	v_mfma_f32_16x16x32_bf16 v[160:163], v[156:159], v[160:163], v[82:85]
	v_mfma_f32_16x16x32_bf16 v[130:133], v[130:133], v[188:191], v[90:93]
	v_mfma_f32_16x16x32_bf16 v[156:159], v[156:159], v[188:191], v[110:113]
	s_waitcnt vmcnt(0)
	s_barrier
; #define MFMA16(a, b, c) __builtin_amdgcn_mfma_f32_16x16x32_bf16((a), (b), (c), 0, 0, 0)
; template <int EPI>
; DI void gemm_tile(const GemmArgs& ga, const EpiArgs& ea, int m0, int n0, char* lds) {
;     ...
;     const char* Ab = lds + (kt % 3) * 24576 + wm * 128 * 64;
;     const char* Bb = lds + (kt % 3) * 24576 + 16384 + wn * 64 * 64;
;     bf16x8 af[8], bfr[4];
;     const int ch = swz64(c16, quad) << 4;
; #pragma unroll
;     for (int nt = 0; nt < 4; ++nt) bfr[nt] = *(const bf16x8*)(Bb + (nt * 16 + c16) * 64 + ch);
; #pragma unroll
;     for (int mt = 0; mt < 2; ++mt) af[mt] = *(const bf16x8*)(Ab + (mt * 16 + c16) * 64 + ch);
;     __builtin_amdgcn_sched_barrier(0);
;     if (kt + 2 < nk) dma(kt + 2, (kt + 2) % 3);
;     __builtin_amdgcn_sched_barrier(0);
; #pragma unroll
;     for (int g = 0; g < 4; ++g) {
;       if (g < 3) {
; #pragma unroll
;         for (int mt = 2 * g + 2; mt < 2 * g + 4; ++mt) af[mt] = *(const bf16x8*)(Ab + (mt * 16 + c16) * 64 + ch);
;       }
; #pragma unroll
;       for (int mt = 2 * g; mt < 2 * g + 2; ++mt)
; #pragma unroll
;         for (int nt = 0; nt < 4; ++nt) acc[mt][nt] = MFMA16(bfr[nt], af[mt], acc[mt][nt]);
;     ...
;   if constexpr (EPI == EPI_INPROJ) {
;     const int slot = n0 >> 9;
;     const int dbase = (slot < 4) ? slot * 512 : (slot - 1) * 512;
;     float* rsc = (float*)(lds + 73728 + 64);
;     rsc[tid] = rsqrtf(rowsum * (1.f / 1024.f) + 1e-6f);
;     __syncthreads();
; #pragma unroll
;     for (int mt = 0; mt < 8; ++mt) {
;       const int row = m0 + wm * 128 + mt * 16 + c16;
;       const float rs = rsc[wm * 128 + mt * 16 + c16];
; #pragma unroll
;       for (int nt = 0; nt < 4; ++nt) {
;         const int cc0 = (n0 & 511) + wn * 64 + nt * 16 + quad * 4;
;         float v[4];
; #pragma unroll
;         for (int r = 0; r < 4; ++r) v[r] = acc[mt][nt][r] * rs;
;         if (slot == 4) {
	ds_read_b128 v[188:191], v147 offset:40960
	ds_read_b128 v[192:195], v147 offset:41984
	ds_read_b128 v[196:199], v147 offset:43008
	ds_read_b128 v[200:203], v147 offset:44032
	ds_read_b128 v[78:81], v164 offset:24576
	ds_read_b128 v[82:85], v164 offset:25600
	s_waitcnt lgkmcnt(1)
	v_mfma_f32_16x16x32_bf16 v[204:207], v[188:191], v[78:81], v[126:129]
	v_mfma_f32_16x16x32_bf16 v[122:125], v[192:195], v[78:81], v[122:125]
	v_mfma_f32_16x16x32_bf16 v[118:121], v[196:199], v[78:81], v[118:121]
	v_mfma_f32_16x16x32_bf16 v[114:117], v[200:203], v[78:81], v[114:117]
	ds_read_b128 v[78:81], v164 offset:26624
	ds_read_b128 v[126:129], v164 offset:27648
	s_waitcnt lgkmcnt(2)
	v_mfma_f32_16x16x32_bf16 v[110:113], v[188:191], v[82:85], v[106:109]
	v_mfma_f32_16x16x32_bf16 v[106:109], v[192:195], v[82:85], v[98:101]
	v_mfma_f32_16x16x32_bf16 v[102:105], v[196:199], v[82:85], v[86:89]
	v_mfma_f32_16x16x32_bf16 v[98:101], v[200:203], v[82:85], v[74:77]
	s_waitcnt lgkmcnt(1)
	v_mfma_f32_16x16x32_bf16 v[94:97], v[188:191], v[78:81], v[70:73]
	s_waitcnt lgkmcnt(0)
	v_mfma_f32_16x16x32_bf16 v[70:73], v[196:199], v[126:129], v[46:49]
	s_nop 2
	ds_read_b128 v[46:49], v164 offset:28672
	ds_read_b128 v[208:211], v164 offset:29696
	v_mfma_f32_16x16x32_bf16 v[90:93], v[192:195], v[78:81], v[66:69]
	v_mfma_f32_16x16x32_bf16 v[86:89], v[196:199], v[78:81], v[62:65]
	v_mfma_f32_16x16x32_bf16 v[82:85], v[200:203], v[78:81], v[58:61]
	v_mfma_f32_16x16x32_bf16 v[78:81], v[188:191], v[126:129], v[54:57]
	v_mfma_f32_16x16x32_bf16 v[74:77], v[192:195], v[126:129], v[50:53]
	v_mfma_f32_16x16x32_bf16 v[66:69], v[200:203], v[126:129], v[42:45]
	s_waitcnt lgkmcnt(1)
	v_mfma_f32_16x16x32_bf16 v[62:65], v[188:191], v[46:49], v[38:41]
	s_waitcnt lgkmcnt(0)
	v_mfma_f32_16x16x32_bf16 v[38:41], v[196:199], v[208:211], v[14:17]
	s_nop 2
	ds_read_b128 v[14:17], v164 offset:30720
	ds_read_b128 v[126:129], v164 offset:31744
	v_mfma_f32_16x16x32_bf16 v[58:61], v[192:195], v[46:49], v[34:37]
	v_mfma_f32_16x16x32_bf16 v[54:57], v[196:199], v[46:49], v[30:33]
	v_mfma_f32_16x16x32_bf16 v[50:53], v[200:203], v[46:49], v[26:29]
	v_mfma_f32_16x16x32_bf16 v[46:49], v[188:191], v[208:211], v[22:25]
	v_mfma_f32_16x16x32_bf16 v[42:45], v[192:195], v[208:211], v[18:21]
	v_mfma_f32_16x16x32_bf16 v[34:37], v[200:203], v[208:211], v[10:13]
	s_waitcnt lgkmcnt(1)
	v_mfma_f32_16x16x32_bf16 v[30:33], v[188:191], v[14:17], v[6:9]
	v_mfma_f32_16x16x32_bf16 v[26:29], v[192:195], v[14:17], v[2:5]
	v_mfma_f32_16x16x32_bf16 v[22:25], v[196:199], v[14:17], v[168:171]
	v_mfma_f32_16x16x32_bf16 v[18:21], v[200:203], v[14:17], v[160:163]
	s_waitcnt lgkmcnt(0)
	v_mfma_f32_16x16x32_bf16 v[14:17], v[188:191], v[126:129], v[130:133]
	v_mfma_f32_16x16x32_bf16 v[10:13], v[192:195], v[126:129], v[134:137]
	v_mfma_f32_16x16x32_bf16 v[6:9], v[196:199], v[126:129], v[138:141]
	v_mfma_f32_16x16x32_bf16 v[2:5], v[200:203], v[126:129], v[156:159]
	v_add_f32_e32 v126, v146, v145
	v_fmamk_f32 v126, v126, 0x3a800000, v175
	s_mov_b32 s9, 0x800000
	v_mul_f32_e32 v127, 0x4b800000, v126
	v_cmp_gt_f32_e32 vcc, s9, v126
	s_and_b32 s24, s23, 0xfffffe00
	s_ashr_i32 s8, s22, 2
	v_cndmask_b32_e32 v126, v126, v127, vcc
	v_rsq_f32_e32 v126, v126
	s_add_i32 s25, s24, 0xfffffe00
	s_cmp_lt_i32 s8, 4
	s_cselect_b32 s24, s24, s25
	v_mul_f32_e32 v127, 0x45800000, v126
	v_cndmask_b32_e32 v126, v126, v127, vcc
	v_lshl_add_u32 v127, v167, 2, s64
	ds_write_b32 v127, v126
	v_and_b32_e32 v127, 0x3fffff8f, v167
	s_and_b32 s23, s23, 0x180
	s_cmp_lg_u32 s8, 4
	v_lshl_add_u32 v169, v127, 2, s64
	s_waitcnt lgkmcnt(0)
	s_barrier
	v_lshlrev_b32_e32 v128, 6, v144
	v_lshlrev_b32_e32 v0, 2, v0
	s_cselect_b64 s[36:37], -1, 0
	s_cmp_eq_u32 s8, 2
	ds_read_b32 v146, v169
	v_or3_b32 v166, v128, s23, v0
	s_cselect_b64 s[28:29], -1, 0
	s_and_b32 s23, s22, 0x1fffff8
	v_and_b32_e32 v126, 0xffffff80, v167
	s_cmp_lg_u32 s23, 8
	v_add_u32_e32 v170, s26, v126
	s_cselect_b64 s[44:45], -1, 0
	s_and_b32 s22, s22, 0x1ffffec
	v_or_b32_e32 v126, v170, v142
	s_cmp_lg_u32 s22, 4
	s_cselect_b64 s[26:27], -1, 0
	v_and_b32_e32 v168, 4, v0
	v_cmp_gt_u32_e64 s[40:41], 32, v143
	s_ashr_i32 s25, s24, 31
	v_mad_i64_i32 v[144:145], s[22:23], v126, s35, 0
	s_waitcnt lgkmcnt(0)
	v_pk_mul_f32 v[138:139], v[204:205], v[146:147] op_sel_hi:[1,0]
	v_pk_mul_f32 v[136:137], v[206:207], v[146:147] op_sel_hi:[1,0]
	s_mov_b64 s[38:39], -1
	s_and_b64 vcc, exec, s[36:37]
	s_cbranch_vccz .LBB0_200
	s_and_b64 vcc, exec, s[44:45]
	s_cbranch_vccz .LBB0_196
	s_andn2_b64 vcc, exec, s[26:27]
	s_cbranch_vccnz .LBB0_193
	s_cmp_lt_i32 s8, 8
	s_cbranch_scc1 .LBB0_187
	s_cmp_gt_i32 s8, 8
	s_cbranch_scc0 .LBB0_188
	s_cmp_eq_u32 s8, 9
	s_mov_b64 s[72:73], 0
	s_cselect_b64 s[38:39], -1, 0
	s_branch .LBB0_189
